# v14 + tap_table k-loop rebuilt: 64 h3 loads per 16-k iteration issued up front (was ~5 k in flight), filter values from LDS two k ahead, same FMA order
# speedup vs baseline: 1.0067x; 1.0057x over previous
.LBB0_543:
	v_lshl_add_u64 v[158:159], v[10:11], 0, s[4:5]
	s_mov_b32 s99, 0
	s_mov_b32 s98, 0x181000
	v_lshl_add_u64 v[200:201], v[158:159], 0, s[98:99]
	global_load_dword v32, v[200:201], off offset:-4096
	global_load_dword v33, v[200:201], off offset:-2048
	global_load_dword v42, v[200:201], off
	global_load_dword v43, v[200:201], off offset:2048
	s_mov_b32 s98, 0x183000
	v_lshl_add_u64 v[200:201], v[158:159], 0, s[98:99]
	global_load_dword v52, v[200:201], off offset:-4096
	global_load_dword v53, v[200:201], off offset:-2048
	global_load_dword v54, v[200:201], off
	global_load_dword v55, v[200:201], off offset:2048
	s_mov_b32 s98, 0x185000
	v_lshl_add_u64 v[200:201], v[158:159], 0, s[98:99]
	global_load_dword v58, v[200:201], off offset:-4096
	global_load_dword v59, v[200:201], off offset:-2048
	global_load_dword v62, v[200:201], off
	global_load_dword v63, v[200:201], off offset:2048
	s_mov_b32 s98, 0x187000
	v_lshl_add_u64 v[200:201], v[158:159], 0, s[98:99]
	global_load_dword v64, v[200:201], off offset:-4096
	global_load_dword v65, v[200:201], off offset:-2048
	global_load_dword v68, v[200:201], off
	global_load_dword v69, v[200:201], off offset:2048
	s_mov_b32 s98, 0x189000
	v_lshl_add_u64 v[200:201], v[158:159], 0, s[98:99]
	global_load_dword v70, v[200:201], off offset:-4096
	global_load_dword v71, v[200:201], off offset:-2048
	global_load_dword v72, v[200:201], off
	global_load_dword v73, v[200:201], off offset:2048
	s_mov_b32 s98, 0x18b000
	v_lshl_add_u64 v[200:201], v[158:159], 0, s[98:99]
	global_load_dword v74, v[200:201], off offset:-4096
	global_load_dword v75, v[200:201], off offset:-2048
	global_load_dword v84, v[200:201], off
	global_load_dword v85, v[200:201], off offset:2048
	s_mov_b32 s98, 0x18d000
	v_lshl_add_u64 v[200:201], v[158:159], 0, s[98:99]
	global_load_dword v94, v[200:201], off offset:-4096
	global_load_dword v95, v[200:201], off offset:-2048
	global_load_dword v104, v[200:201], off
	global_load_dword v105, v[200:201], off offset:2048
	s_mov_b32 s98, 0x18f000
	v_lshl_add_u64 v[200:201], v[158:159], 0, s[98:99]
	global_load_dword v112, v[200:201], off offset:-4096
	global_load_dword v113, v[200:201], off offset:-2048
	global_load_dword v116, v[200:201], off
	global_load_dword v117, v[200:201], off offset:2048
	s_mov_b32 s98, 0x191000
	v_lshl_add_u64 v[200:201], v[158:159], 0, s[98:99]
	global_load_dword v122, v[200:201], off offset:-4096
	global_load_dword v123, v[200:201], off offset:-2048
	global_load_dword v126, v[200:201], off
	global_load_dword v127, v[200:201], off offset:2048
	s_mov_b32 s98, 0x193000
	v_lshl_add_u64 v[200:201], v[158:159], 0, s[98:99]
	global_load_dword v130, v[200:201], off offset:-4096
	global_load_dword v131, v[200:201], off offset:-2048
	global_load_dword v138, v[200:201], off
	global_load_dword v139, v[200:201], off offset:2048
	s_mov_b32 s98, 0x195000
	v_lshl_add_u64 v[200:201], v[158:159], 0, s[98:99]
	global_load_dword v140, v[200:201], off offset:-4096
	global_load_dword v141, v[200:201], off offset:-2048
	global_load_dword v144, v[200:201], off
	global_load_dword v145, v[200:201], off offset:2048
	s_mov_b32 s98, 0x197000
	v_lshl_add_u64 v[200:201], v[158:159], 0, s[98:99]
	global_load_dword v150, v[200:201], off offset:-4096
	global_load_dword v151, v[200:201], off offset:-2048
	global_load_dword v154, v[200:201], off
	global_load_dword v155, v[200:201], off offset:2048
	s_mov_b32 s98, 0x199000
	v_lshl_add_u64 v[200:201], v[158:159], 0, s[98:99]
	global_load_dword v156, v[200:201], off offset:-4096
	global_load_dword v157, v[200:201], off offset:-2048
	global_load_dword v160, v[200:201], off
	global_load_dword v161, v[200:201], off offset:2048
	s_mov_b32 s98, 0x19b000
	v_lshl_add_u64 v[200:201], v[158:159], 0, s[98:99]
	global_load_dword v162, v[200:201], off offset:-4096
	global_load_dword v163, v[200:201], off offset:-2048
	global_load_dword v164, v[200:201], off
	global_load_dword v165, v[200:201], off offset:2048
	s_mov_b32 s98, 0x19d000
	v_lshl_add_u64 v[200:201], v[158:159], 0, s[98:99]
	global_load_dword v166, v[200:201], off offset:-4096
	global_load_dword v167, v[200:201], off offset:-2048
	global_load_dword v168, v[200:201], off
	global_load_dword v169, v[200:201], off offset:2048
	s_mov_b32 s98, 0x19f000
	v_lshl_add_u64 v[200:201], v[158:159], 0, s[98:99]
	global_load_dword v170, v[200:201], off offset:-4096
	global_load_dword v171, v[200:201], off offset:-2048
	global_load_dword v172, v[200:201], off
	global_load_dword v173, v[200:201], off offset:2048
	ds_read_b64 v[174:175], v253 offset:0
	ds_read_b64 v[176:177], v253 offset:8
	ds_read_b64 v[180:181], v253 offset:16
	ds_read_b64 v[182:183], v253 offset:24
	ds_read_b64 v[184:185], v253 offset:32
	ds_read_b64 v[186:187], v253 offset:40
	ds_read_b64 v[188:189], v253 offset:48
	ds_read_b64 v[190:191], v253 offset:56
	ds_read_b64 v[192:193], v253 offset:64
	ds_read_b64 v[194:195], v253 offset:72
	ds_read_b64 v[196:197], v253 offset:80
	ds_read_b64 v[198:199], v253 offset:88
	s_waitcnt vmcnt(60) lgkmcnt(8)
	v_pk_fma_f32 v[50:51], v[32:33], v[174:175], v[50:51] op_sel_hi:[0,1,1]
	v_pk_fma_f32 v[26:27], v[32:33], v[174:175], v[26:27] op_sel:[1,0,0] op_sel_hi:[1,1,1]
	v_pk_fma_f32 v[22:23], v[42:43], v[174:175], v[22:23] op_sel_hi:[0,1,1]
	v_pk_fma_f32 v[20:21], v[42:43], v[174:175], v[20:21] op_sel:[1,0,0] op_sel_hi:[1,1,1]
	v_pk_fma_f32 v[38:39], v[32:33], v[176:177], v[38:39] op_sel_hi:[0,1,1]
	v_pk_fma_f32 v[30:31], v[32:33], v[176:177], v[30:31] op_sel:[1,0,0] op_sel_hi:[1,1,1]
	v_pk_fma_f32 v[28:29], v[42:43], v[176:177], v[28:29] op_sel_hi:[0,1,1]
	v_pk_fma_f32 v[24:25], v[42:43], v[176:177], v[24:25] op_sel:[1,0,0] op_sel_hi:[1,1,1]
	v_pk_fma_f32 v[48:49], v[32:33], v[180:181], v[48:49] op_sel_hi:[0,1,1]
	v_pk_fma_f32 v[46:47], v[32:33], v[180:181], v[46:47] op_sel:[1,0,0] op_sel_hi:[1,1,1]
	v_pk_fma_f32 v[44:45], v[42:43], v[180:181], v[44:45] op_sel_hi:[0,1,1]
	v_pk_fma_f32 v[40:41], v[42:43], v[180:181], v[40:41] op_sel:[1,0,0] op_sel_hi:[1,1,1]
	v_pk_fma_f32 v[18:19], v[32:33], v[182:183], v[18:19] op_sel_hi:[0,1,1]
	v_pk_fma_f32 v[16:17], v[32:33], v[182:183], v[16:17] op_sel:[1,0,0] op_sel_hi:[1,1,1]
	v_pk_fma_f32 v[14:15], v[42:43], v[182:183], v[14:15] op_sel_hi:[0,1,1]
	v_pk_fma_f32 v[12:13], v[42:43], v[182:183], v[12:13] op_sel:[1,0,0] op_sel_hi:[1,1,1]
	ds_read_b64 v[174:175], v253 offset:96
	ds_read_b64 v[176:177], v253 offset:104
	ds_read_b64 v[180:181], v253 offset:112
	ds_read_b64 v[182:183], v253 offset:120
	s_waitcnt vmcnt(56) lgkmcnt(8)
	v_pk_fma_f32 v[50:51], v[52:53], v[184:185], v[50:51] op_sel_hi:[0,1,1]
	v_pk_fma_f32 v[26:27], v[52:53], v[184:185], v[26:27] op_sel:[1,0,0] op_sel_hi:[1,1,1]
	v_pk_fma_f32 v[22:23], v[54:55], v[184:185], v[22:23] op_sel_hi:[0,1,1]
	v_pk_fma_f32 v[20:21], v[54:55], v[184:185], v[20:21] op_sel:[1,0,0] op_sel_hi:[1,1,1]
	v_pk_fma_f32 v[38:39], v[52:53], v[186:187], v[38:39] op_sel_hi:[0,1,1]
	v_pk_fma_f32 v[30:31], v[52:53], v[186:187], v[30:31] op_sel:[1,0,0] op_sel_hi:[1,1,1]
	v_pk_fma_f32 v[28:29], v[54:55], v[186:187], v[28:29] op_sel_hi:[0,1,1]
	v_pk_fma_f32 v[24:25], v[54:55], v[186:187], v[24:25] op_sel:[1,0,0] op_sel_hi:[1,1,1]
	v_pk_fma_f32 v[48:49], v[52:53], v[188:189], v[48:49] op_sel_hi:[0,1,1]
	v_pk_fma_f32 v[46:47], v[52:53], v[188:189], v[46:47] op_sel:[1,0,0] op_sel_hi:[1,1,1]
	v_pk_fma_f32 v[44:45], v[54:55], v[188:189], v[44:45] op_sel_hi:[0,1,1]
	v_pk_fma_f32 v[40:41], v[54:55], v[188:189], v[40:41] op_sel:[1,0,0] op_sel_hi:[1,1,1]
	v_pk_fma_f32 v[18:19], v[52:53], v[190:191], v[18:19] op_sel_hi:[0,1,1]
	v_pk_fma_f32 v[16:17], v[52:53], v[190:191], v[16:17] op_sel:[1,0,0] op_sel_hi:[1,1,1]
	v_pk_fma_f32 v[14:15], v[54:55], v[190:191], v[14:15] op_sel_hi:[0,1,1]
	v_pk_fma_f32 v[12:13], v[54:55], v[190:191], v[12:13] op_sel:[1,0,0] op_sel_hi:[1,1,1]
	ds_read_b64 v[184:185], v253 offset:128
	ds_read_b64 v[186:187], v253 offset:136
	ds_read_b64 v[188:189], v253 offset:144
	ds_read_b64 v[190:191], v253 offset:152
	s_waitcnt vmcnt(52) lgkmcnt(8)
	v_pk_fma_f32 v[50:51], v[58:59], v[192:193], v[50:51] op_sel_hi:[0,1,1]
	v_pk_fma_f32 v[26:27], v[58:59], v[192:193], v[26:27] op_sel:[1,0,0] op_sel_hi:[1,1,1]
	v_pk_fma_f32 v[22:23], v[62:63], v[192:193], v[22:23] op_sel_hi:[0,1,1]
	v_pk_fma_f32 v[20:21], v[62:63], v[192:193], v[20:21] op_sel:[1,0,0] op_sel_hi:[1,1,1]
	v_pk_fma_f32 v[38:39], v[58:59], v[194:195], v[38:39] op_sel_hi:[0,1,1]
	v_pk_fma_f32 v[30:31], v[58:59], v[194:195], v[30:31] op_sel:[1,0,0] op_sel_hi:[1,1,1]
	v_pk_fma_f32 v[28:29], v[62:63], v[194:195], v[28:29] op_sel_hi:[0,1,1]
	v_pk_fma_f32 v[24:25], v[62:63], v[194:195], v[24:25] op_sel:[1,0,0] op_sel_hi:[1,1,1]
	v_pk_fma_f32 v[48:49], v[58:59], v[196:197], v[48:49] op_sel_hi:[0,1,1]
	v_pk_fma_f32 v[46:47], v[58:59], v[196:197], v[46:47] op_sel:[1,0,0] op_sel_hi:[1,1,1]
	v_pk_fma_f32 v[44:45], v[62:63], v[196:197], v[44:45] op_sel_hi:[0,1,1]
	v_pk_fma_f32 v[40:41], v[62:63], v[196:197], v[40:41] op_sel:[1,0,0] op_sel_hi:[1,1,1]
	v_pk_fma_f32 v[18:19], v[58:59], v[198:199], v[18:19] op_sel_hi:[0,1,1]
	v_pk_fma_f32 v[16:17], v[58:59], v[198:199], v[16:17] op_sel:[1,0,0] op_sel_hi:[1,1,1]
	v_pk_fma_f32 v[14:15], v[62:63], v[198:199], v[14:15] op_sel_hi:[0,1,1]
	v_pk_fma_f32 v[12:13], v[62:63], v[198:199], v[12:13] op_sel:[1,0,0] op_sel_hi:[1,1,1]
	ds_read_b64 v[192:193], v253 offset:160
	ds_read_b64 v[194:195], v253 offset:168
	ds_read_b64 v[196:197], v253 offset:176
	ds_read_b64 v[198:199], v253 offset:184
	s_waitcnt vmcnt(48) lgkmcnt(8)
	v_pk_fma_f32 v[50:51], v[64:65], v[174:175], v[50:51] op_sel_hi:[0,1,1]
	v_pk_fma_f32 v[26:27], v[64:65], v[174:175], v[26:27] op_sel:[1,0,0] op_sel_hi:[1,1,1]
	v_pk_fma_f32 v[22:23], v[68:69], v[174:175], v[22:23] op_sel_hi:[0,1,1]
	v_pk_fma_f32 v[20:21], v[68:69], v[174:175], v[20:21] op_sel:[1,0,0] op_sel_hi:[1,1,1]
	v_pk_fma_f32 v[38:39], v[64:65], v[176:177], v[38:39] op_sel_hi:[0,1,1]
	v_pk_fma_f32 v[30:31], v[64:65], v[176:177], v[30:31] op_sel:[1,0,0] op_sel_hi:[1,1,1]
	v_pk_fma_f32 v[28:29], v[68:69], v[176:177], v[28:29] op_sel_hi:[0,1,1]
	v_pk_fma_f32 v[24:25], v[68:69], v[176:177], v[24:25] op_sel:[1,0,0] op_sel_hi:[1,1,1]
	v_pk_fma_f32 v[48:49], v[64:65], v[180:181], v[48:49] op_sel_hi:[0,1,1]
	v_pk_fma_f32 v[46:47], v[64:65], v[180:181], v[46:47] op_sel:[1,0,0] op_sel_hi:[1,1,1]
	v_pk_fma_f32 v[44:45], v[68:69], v[180:181], v[44:45] op_sel_hi:[0,1,1]
	v_pk_fma_f32 v[40:41], v[68:69], v[180:181], v[40:41] op_sel:[1,0,0] op_sel_hi:[1,1,1]
	v_pk_fma_f32 v[18:19], v[64:65], v[182:183], v[18:19] op_sel_hi:[0,1,1]
	v_pk_fma_f32 v[16:17], v[64:65], v[182:183], v[16:17] op_sel:[1,0,0] op_sel_hi:[1,1,1]
	v_pk_fma_f32 v[14:15], v[68:69], v[182:183], v[14:15] op_sel_hi:[0,1,1]
	v_pk_fma_f32 v[12:13], v[68:69], v[182:183], v[12:13] op_sel:[1,0,0] op_sel_hi:[1,1,1]
	ds_read_b64 v[174:175], v253 offset:192
	ds_read_b64 v[176:177], v253 offset:200
	ds_read_b64 v[180:181], v253 offset:208
	ds_read_b64 v[182:183], v253 offset:216
	s_waitcnt vmcnt(44) lgkmcnt(8)
	v_pk_fma_f32 v[50:51], v[70:71], v[184:185], v[50:51] op_sel_hi:[0,1,1]
	v_pk_fma_f32 v[26:27], v[70:71], v[184:185], v[26:27] op_sel:[1,0,0] op_sel_hi:[1,1,1]
	v_pk_fma_f32 v[22:23], v[72:73], v[184:185], v[22:23] op_sel_hi:[0,1,1]
	v_pk_fma_f32 v[20:21], v[72:73], v[184:185], v[20:21] op_sel:[1,0,0] op_sel_hi:[1,1,1]
	v_pk_fma_f32 v[38:39], v[70:71], v[186:187], v[38:39] op_sel_hi:[0,1,1]
	v_pk_fma_f32 v[30:31], v[70:71], v[186:187], v[30:31] op_sel:[1,0,0] op_sel_hi:[1,1,1]
	v_pk_fma_f32 v[28:29], v[72:73], v[186:187], v[28:29] op_sel_hi:[0,1,1]
	v_pk_fma_f32 v[24:25], v[72:73], v[186:187], v[24:25] op_sel:[1,0,0] op_sel_hi:[1,1,1]
	v_pk_fma_f32 v[48:49], v[70:71], v[188:189], v[48:49] op_sel_hi:[0,1,1]
	v_pk_fma_f32 v[46:47], v[70:71], v[188:189], v[46:47] op_sel:[1,0,0] op_sel_hi:[1,1,1]
	v_pk_fma_f32 v[44:45], v[72:73], v[188:189], v[44:45] op_sel_hi:[0,1,1]
	v_pk_fma_f32 v[40:41], v[72:73], v[188:189], v[40:41] op_sel:[1,0,0] op_sel_hi:[1,1,1]
	v_pk_fma_f32 v[18:19], v[70:71], v[190:191], v[18:19] op_sel_hi:[0,1,1]
	v_pk_fma_f32 v[16:17], v[70:71], v[190:191], v[16:17] op_sel:[1,0,0] op_sel_hi:[1,1,1]
	v_pk_fma_f32 v[14:15], v[72:73], v[190:191], v[14:15] op_sel_hi:[0,1,1]
	v_pk_fma_f32 v[12:13], v[72:73], v[190:191], v[12:13] op_sel:[1,0,0] op_sel_hi:[1,1,1]
	ds_read_b64 v[184:185], v253 offset:224
	ds_read_b64 v[186:187], v253 offset:232
	ds_read_b64 v[188:189], v253 offset:240
	ds_read_b64 v[190:191], v253 offset:248
	s_waitcnt vmcnt(40) lgkmcnt(8)
	v_pk_fma_f32 v[50:51], v[74:75], v[192:193], v[50:51] op_sel_hi:[0,1,1]
	v_pk_fma_f32 v[26:27], v[74:75], v[192:193], v[26:27] op_sel:[1,0,0] op_sel_hi:[1,1,1]
	v_pk_fma_f32 v[22:23], v[84:85], v[192:193], v[22:23] op_sel_hi:[0,1,1]
	v_pk_fma_f32 v[20:21], v[84:85], v[192:193], v[20:21] op_sel:[1,0,0] op_sel_hi:[1,1,1]
	v_pk_fma_f32 v[38:39], v[74:75], v[194:195], v[38:39] op_sel_hi:[0,1,1]
	v_pk_fma_f32 v[30:31], v[74:75], v[194:195], v[30:31] op_sel:[1,0,0] op_sel_hi:[1,1,1]
	v_pk_fma_f32 v[28:29], v[84:85], v[194:195], v[28:29] op_sel_hi:[0,1,1]
	v_pk_fma_f32 v[24:25], v[84:85], v[194:195], v[24:25] op_sel:[1,0,0] op_sel_hi:[1,1,1]
	v_pk_fma_f32 v[48:49], v[74:75], v[196:197], v[48:49] op_sel_hi:[0,1,1]
	v_pk_fma_f32 v[46:47], v[74:75], v[196:197], v[46:47] op_sel:[1,0,0] op_sel_hi:[1,1,1]
	v_pk_fma_f32 v[44:45], v[84:85], v[196:197], v[44:45] op_sel_hi:[0,1,1]
	v_pk_fma_f32 v[40:41], v[84:85], v[196:197], v[40:41] op_sel:[1,0,0] op_sel_hi:[1,1,1]
	v_pk_fma_f32 v[18:19], v[74:75], v[198:199], v[18:19] op_sel_hi:[0,1,1]
	v_pk_fma_f32 v[16:17], v[74:75], v[198:199], v[16:17] op_sel:[1,0,0] op_sel_hi:[1,1,1]
	v_pk_fma_f32 v[14:15], v[84:85], v[198:199], v[14:15] op_sel_hi:[0,1,1]
	v_pk_fma_f32 v[12:13], v[84:85], v[198:199], v[12:13] op_sel:[1,0,0] op_sel_hi:[1,1,1]
	ds_read_b64 v[192:193], v253 offset:256
	ds_read_b64 v[194:195], v253 offset:264
	ds_read_b64 v[196:197], v253 offset:272
	ds_read_b64 v[198:199], v253 offset:280
	s_waitcnt vmcnt(36) lgkmcnt(8)
	v_pk_fma_f32 v[50:51], v[94:95], v[174:175], v[50:51] op_sel_hi:[0,1,1]
	v_pk_fma_f32 v[26:27], v[94:95], v[174:175], v[26:27] op_sel:[1,0,0] op_sel_hi:[1,1,1]
	v_pk_fma_f32 v[22:23], v[104:105], v[174:175], v[22:23] op_sel_hi:[0,1,1]
	v_pk_fma_f32 v[20:21], v[104:105], v[174:175], v[20:21] op_sel:[1,0,0] op_sel_hi:[1,1,1]
	v_pk_fma_f32 v[38:39], v[94:95], v[176:177], v[38:39] op_sel_hi:[0,1,1]
	v_pk_fma_f32 v[30:31], v[94:95], v[176:177], v[30:31] op_sel:[1,0,0] op_sel_hi:[1,1,1]
	v_pk_fma_f32 v[28:29], v[104:105], v[176:177], v[28:29] op_sel_hi:[0,1,1]
	v_pk_fma_f32 v[24:25], v[104:105], v[176:177], v[24:25] op_sel:[1,0,0] op_sel_hi:[1,1,1]
	v_pk_fma_f32 v[48:49], v[94:95], v[180:181], v[48:49] op_sel_hi:[0,1,1]
	v_pk_fma_f32 v[46:47], v[94:95], v[180:181], v[46:47] op_sel:[1,0,0] op_sel_hi:[1,1,1]
	v_pk_fma_f32 v[44:45], v[104:105], v[180:181], v[44:45] op_sel_hi:[0,1,1]
	v_pk_fma_f32 v[40:41], v[104:105], v[180:181], v[40:41] op_sel:[1,0,0] op_sel_hi:[1,1,1]
	v_pk_fma_f32 v[18:19], v[94:95], v[182:183], v[18:19] op_sel_hi:[0,1,1]
	v_pk_fma_f32 v[16:17], v[94:95], v[182:183], v[16:17] op_sel:[1,0,0] op_sel_hi:[1,1,1]
	v_pk_fma_f32 v[14:15], v[104:105], v[182:183], v[14:15] op_sel_hi:[0,1,1]
	v_pk_fma_f32 v[12:13], v[104:105], v[182:183], v[12:13] op_sel:[1,0,0] op_sel_hi:[1,1,1]
	ds_read_b64 v[174:175], v253 offset:288
	ds_read_b64 v[176:177], v253 offset:296
	ds_read_b64 v[180:181], v253 offset:304
	ds_read_b64 v[182:183], v253 offset:312
	s_waitcnt vmcnt(32) lgkmcnt(8)
	v_pk_fma_f32 v[50:51], v[112:113], v[184:185], v[50:51] op_sel_hi:[0,1,1]
	v_pk_fma_f32 v[26:27], v[112:113], v[184:185], v[26:27] op_sel:[1,0,0] op_sel_hi:[1,1,1]
	v_pk_fma_f32 v[22:23], v[116:117], v[184:185], v[22:23] op_sel_hi:[0,1,1]
	v_pk_fma_f32 v[20:21], v[116:117], v[184:185], v[20:21] op_sel:[1,0,0] op_sel_hi:[1,1,1]
	v_pk_fma_f32 v[38:39], v[112:113], v[186:187], v[38:39] op_sel_hi:[0,1,1]
	v_pk_fma_f32 v[30:31], v[112:113], v[186:187], v[30:31] op_sel:[1,0,0] op_sel_hi:[1,1,1]
	v_pk_fma_f32 v[28:29], v[116:117], v[186:187], v[28:29] op_sel_hi:[0,1,1]
	v_pk_fma_f32 v[24:25], v[116:117], v[186:187], v[24:25] op_sel:[1,0,0] op_sel_hi:[1,1,1]
	v_pk_fma_f32 v[48:49], v[112:113], v[188:189], v[48:49] op_sel_hi:[0,1,1]
	v_pk_fma_f32 v[46:47], v[112:113], v[188:189], v[46:47] op_sel:[1,0,0] op_sel_hi:[1,1,1]
	v_pk_fma_f32 v[44:45], v[116:117], v[188:189], v[44:45] op_sel_hi:[0,1,1]
	v_pk_fma_f32 v[40:41], v[116:117], v[188:189], v[40:41] op_sel:[1,0,0] op_sel_hi:[1,1,1]
	v_pk_fma_f32 v[18:19], v[112:113], v[190:191], v[18:19] op_sel_hi:[0,1,1]
	v_pk_fma_f32 v[16:17], v[112:113], v[190:191], v[16:17] op_sel:[1,0,0] op_sel_hi:[1,1,1]
	v_pk_fma_f32 v[14:15], v[116:117], v[190:191], v[14:15] op_sel_hi:[0,1,1]
	v_pk_fma_f32 v[12:13], v[116:117], v[190:191], v[12:13] op_sel:[1,0,0] op_sel_hi:[1,1,1]
	ds_read_b64 v[184:185], v253 offset:320
	ds_read_b64 v[186:187], v253 offset:328
	ds_read_b64 v[188:189], v253 offset:336
	ds_read_b64 v[190:191], v253 offset:344
	s_waitcnt vmcnt(28) lgkmcnt(8)
	v_pk_fma_f32 v[50:51], v[122:123], v[192:193], v[50:51] op_sel_hi:[0,1,1]
	v_pk_fma_f32 v[26:27], v[122:123], v[192:193], v[26:27] op_sel:[1,0,0] op_sel_hi:[1,1,1]
	v_pk_fma_f32 v[22:23], v[126:127], v[192:193], v[22:23] op_sel_hi:[0,1,1]
	v_pk_fma_f32 v[20:21], v[126:127], v[192:193], v[20:21] op_sel:[1,0,0] op_sel_hi:[1,1,1]
	v_pk_fma_f32 v[38:39], v[122:123], v[194:195], v[38:39] op_sel_hi:[0,1,1]
	v_pk_fma_f32 v[30:31], v[122:123], v[194:195], v[30:31] op_sel:[1,0,0] op_sel_hi:[1,1,1]
	v_pk_fma_f32 v[28:29], v[126:127], v[194:195], v[28:29] op_sel_hi:[0,1,1]
	v_pk_fma_f32 v[24:25], v[126:127], v[194:195], v[24:25] op_sel:[1,0,0] op_sel_hi:[1,1,1]
	v_pk_fma_f32 v[48:49], v[122:123], v[196:197], v[48:49] op_sel_hi:[0,1,1]
	v_pk_fma_f32 v[46:47], v[122:123], v[196:197], v[46:47] op_sel:[1,0,0] op_sel_hi:[1,1,1]
	v_pk_fma_f32 v[44:45], v[126:127], v[196:197], v[44:45] op_sel_hi:[0,1,1]
	v_pk_fma_f32 v[40:41], v[126:127], v[196:197], v[40:41] op_sel:[1,0,0] op_sel_hi:[1,1,1]
	v_pk_fma_f32 v[18:19], v[122:123], v[198:199], v[18:19] op_sel_hi:[0,1,1]
	v_pk_fma_f32 v[16:17], v[122:123], v[198:199], v[16:17] op_sel:[1,0,0] op_sel_hi:[1,1,1]
	v_pk_fma_f32 v[14:15], v[126:127], v[198:199], v[14:15] op_sel_hi:[0,1,1]
	v_pk_fma_f32 v[12:13], v[126:127], v[198:199], v[12:13] op_sel:[1,0,0] op_sel_hi:[1,1,1]
	ds_read_b64 v[192:193], v253 offset:352
	ds_read_b64 v[194:195], v253 offset:360
	ds_read_b64 v[196:197], v253 offset:368
	ds_read_b64 v[198:199], v253 offset:376
	s_waitcnt vmcnt(24) lgkmcnt(8)
	v_pk_fma_f32 v[50:51], v[130:131], v[174:175], v[50:51] op_sel_hi:[0,1,1]
	v_pk_fma_f32 v[26:27], v[130:131], v[174:175], v[26:27] op_sel:[1,0,0] op_sel_hi:[1,1,1]
	v_pk_fma_f32 v[22:23], v[138:139], v[174:175], v[22:23] op_sel_hi:[0,1,1]
	v_pk_fma_f32 v[20:21], v[138:139], v[174:175], v[20:21] op_sel:[1,0,0] op_sel_hi:[1,1,1]
	v_pk_fma_f32 v[38:39], v[130:131], v[176:177], v[38:39] op_sel_hi:[0,1,1]
	v_pk_fma_f32 v[30:31], v[130:131], v[176:177], v[30:31] op_sel:[1,0,0] op_sel_hi:[1,1,1]
	v_pk_fma_f32 v[28:29], v[138:139], v[176:177], v[28:29] op_sel_hi:[0,1,1]
	v_pk_fma_f32 v[24:25], v[138:139], v[176:177], v[24:25] op_sel:[1,0,0] op_sel_hi:[1,1,1]
	v_pk_fma_f32 v[48:49], v[130:131], v[180:181], v[48:49] op_sel_hi:[0,1,1]
	v_pk_fma_f32 v[46:47], v[130:131], v[180:181], v[46:47] op_sel:[1,0,0] op_sel_hi:[1,1,1]
	v_pk_fma_f32 v[44:45], v[138:139], v[180:181], v[44:45] op_sel_hi:[0,1,1]
	v_pk_fma_f32 v[40:41], v[138:139], v[180:181], v[40:41] op_sel:[1,0,0] op_sel_hi:[1,1,1]
	v_pk_fma_f32 v[18:19], v[130:131], v[182:183], v[18:19] op_sel_hi:[0,1,1]
	v_pk_fma_f32 v[16:17], v[130:131], v[182:183], v[16:17] op_sel:[1,0,0] op_sel_hi:[1,1,1]
	v_pk_fma_f32 v[14:15], v[138:139], v[182:183], v[14:15] op_sel_hi:[0,1,1]
	v_pk_fma_f32 v[12:13], v[138:139], v[182:183], v[12:13] op_sel:[1,0,0] op_sel_hi:[1,1,1]
	ds_read_b64 v[174:175], v253 offset:384
	ds_read_b64 v[176:177], v253 offset:392
	ds_read_b64 v[180:181], v253 offset:400
	ds_read_b64 v[182:183], v253 offset:408
	s_waitcnt vmcnt(20) lgkmcnt(8)
	v_pk_fma_f32 v[50:51], v[140:141], v[184:185], v[50:51] op_sel_hi:[0,1,1]
	v_pk_fma_f32 v[26:27], v[140:141], v[184:185], v[26:27] op_sel:[1,0,0] op_sel_hi:[1,1,1]
	v_pk_fma_f32 v[22:23], v[144:145], v[184:185], v[22:23] op_sel_hi:[0,1,1]
	v_pk_fma_f32 v[20:21], v[144:145], v[184:185], v[20:21] op_sel:[1,0,0] op_sel_hi:[1,1,1]
	v_pk_fma_f32 v[38:39], v[140:141], v[186:187], v[38:39] op_sel_hi:[0,1,1]
	v_pk_fma_f32 v[30:31], v[140:141], v[186:187], v[30:31] op_sel:[1,0,0] op_sel_hi:[1,1,1]
	v_pk_fma_f32 v[28:29], v[144:145], v[186:187], v[28:29] op_sel_hi:[0,1,1]
	v_pk_fma_f32 v[24:25], v[144:145], v[186:187], v[24:25] op_sel:[1,0,0] op_sel_hi:[1,1,1]
	v_pk_fma_f32 v[48:49], v[140:141], v[188:189], v[48:49] op_sel_hi:[0,1,1]
	v_pk_fma_f32 v[46:47], v[140:141], v[188:189], v[46:47] op_sel:[1,0,0] op_sel_hi:[1,1,1]
	v_pk_fma_f32 v[44:45], v[144:145], v[188:189], v[44:45] op_sel_hi:[0,1,1]
	v_pk_fma_f32 v[40:41], v[144:145], v[188:189], v[40:41] op_sel:[1,0,0] op_sel_hi:[1,1,1]
	v_pk_fma_f32 v[18:19], v[140:141], v[190:191], v[18:19] op_sel_hi:[0,1,1]
	v_pk_fma_f32 v[16:17], v[140:141], v[190:191], v[16:17] op_sel:[1,0,0] op_sel_hi:[1,1,1]
	v_pk_fma_f32 v[14:15], v[144:145], v[190:191], v[14:15] op_sel_hi:[0,1,1]
	v_pk_fma_f32 v[12:13], v[144:145], v[190:191], v[12:13] op_sel:[1,0,0] op_sel_hi:[1,1,1]
	ds_read_b64 v[184:185], v253 offset:416
	ds_read_b64 v[186:187], v253 offset:424
	ds_read_b64 v[188:189], v253 offset:432
	ds_read_b64 v[190:191], v253 offset:440
	s_waitcnt vmcnt(16) lgkmcnt(8)
	v_pk_fma_f32 v[50:51], v[150:151], v[192:193], v[50:51] op_sel_hi:[0,1,1]
	v_pk_fma_f32 v[26:27], v[150:151], v[192:193], v[26:27] op_sel:[1,0,0] op_sel_hi:[1,1,1]
	v_pk_fma_f32 v[22:23], v[154:155], v[192:193], v[22:23] op_sel_hi:[0,1,1]
	v_pk_fma_f32 v[20:21], v[154:155], v[192:193], v[20:21] op_sel:[1,0,0] op_sel_hi:[1,1,1]
	v_pk_fma_f32 v[38:39], v[150:151], v[194:195], v[38:39] op_sel_hi:[0,1,1]
	v_pk_fma_f32 v[30:31], v[150:151], v[194:195], v[30:31] op_sel:[1,0,0] op_sel_hi:[1,1,1]
	v_pk_fma_f32 v[28:29], v[154:155], v[194:195], v[28:29] op_sel_hi:[0,1,1]
	v_pk_fma_f32 v[24:25], v[154:155], v[194:195], v[24:25] op_sel:[1,0,0] op_sel_hi:[1,1,1]
	v_pk_fma_f32 v[48:49], v[150:151], v[196:197], v[48:49] op_sel_hi:[0,1,1]
	v_pk_fma_f32 v[46:47], v[150:151], v[196:197], v[46:47] op_sel:[1,0,0] op_sel_hi:[1,1,1]
	v_pk_fma_f32 v[44:45], v[154:155], v[196:197], v[44:45] op_sel_hi:[0,1,1]
	v_pk_fma_f32 v[40:41], v[154:155], v[196:197], v[40:41] op_sel:[1,0,0] op_sel_hi:[1,1,1]
	v_pk_fma_f32 v[18:19], v[150:151], v[198:199], v[18:19] op_sel_hi:[0,1,1]
	v_pk_fma_f32 v[16:17], v[150:151], v[198:199], v[16:17] op_sel:[1,0,0] op_sel_hi:[1,1,1]
	v_pk_fma_f32 v[14:15], v[154:155], v[198:199], v[14:15] op_sel_hi:[0,1,1]
	v_pk_fma_f32 v[12:13], v[154:155], v[198:199], v[12:13] op_sel:[1,0,0] op_sel_hi:[1,1,1]
	ds_read_b64 v[192:193], v253 offset:448
	ds_read_b64 v[194:195], v253 offset:456
	ds_read_b64 v[196:197], v253 offset:464
	ds_read_b64 v[198:199], v253 offset:472
	s_waitcnt vmcnt(12) lgkmcnt(8)
	v_pk_fma_f32 v[50:51], v[156:157], v[174:175], v[50:51] op_sel_hi:[0,1,1]
	v_pk_fma_f32 v[26:27], v[156:157], v[174:175], v[26:27] op_sel:[1,0,0] op_sel_hi:[1,1,1]
	v_pk_fma_f32 v[22:23], v[160:161], v[174:175], v[22:23] op_sel_hi:[0,1,1]
	v_pk_fma_f32 v[20:21], v[160:161], v[174:175], v[20:21] op_sel:[1,0,0] op_sel_hi:[1,1,1]
	v_pk_fma_f32 v[38:39], v[156:157], v[176:177], v[38:39] op_sel_hi:[0,1,1]
	v_pk_fma_f32 v[30:31], v[156:157], v[176:177], v[30:31] op_sel:[1,0,0] op_sel_hi:[1,1,1]
	v_pk_fma_f32 v[28:29], v[160:161], v[176:177], v[28:29] op_sel_hi:[0,1,1]
	v_pk_fma_f32 v[24:25], v[160:161], v[176:177], v[24:25] op_sel:[1,0,0] op_sel_hi:[1,1,1]
	v_pk_fma_f32 v[48:49], v[156:157], v[180:181], v[48:49] op_sel_hi:[0,1,1]
	v_pk_fma_f32 v[46:47], v[156:157], v[180:181], v[46:47] op_sel:[1,0,0] op_sel_hi:[1,1,1]
	v_pk_fma_f32 v[44:45], v[160:161], v[180:181], v[44:45] op_sel_hi:[0,1,1]
	v_pk_fma_f32 v[40:41], v[160:161], v[180:181], v[40:41] op_sel:[1,0,0] op_sel_hi:[1,1,1]
	v_pk_fma_f32 v[18:19], v[156:157], v[182:183], v[18:19] op_sel_hi:[0,1,1]
	v_pk_fma_f32 v[16:17], v[156:157], v[182:183], v[16:17] op_sel:[1,0,0] op_sel_hi:[1,1,1]
	v_pk_fma_f32 v[14:15], v[160:161], v[182:183], v[14:15] op_sel_hi:[0,1,1]
	v_pk_fma_f32 v[12:13], v[160:161], v[182:183], v[12:13] op_sel:[1,0,0] op_sel_hi:[1,1,1]
	ds_read_b64 v[174:175], v253 offset:480
	ds_read_b64 v[176:177], v253 offset:488
	ds_read_b64 v[180:181], v253 offset:496
	ds_read_b64 v[182:183], v253 offset:504
	s_waitcnt vmcnt(8) lgkmcnt(8)
	v_pk_fma_f32 v[50:51], v[162:163], v[184:185], v[50:51] op_sel_hi:[0,1,1]
	v_pk_fma_f32 v[26:27], v[162:163], v[184:185], v[26:27] op_sel:[1,0,0] op_sel_hi:[1,1,1]
	v_pk_fma_f32 v[22:23], v[164:165], v[184:185], v[22:23] op_sel_hi:[0,1,1]
	v_pk_fma_f32 v[20:21], v[164:165], v[184:185], v[20:21] op_sel:[1,0,0] op_sel_hi:[1,1,1]
	v_pk_fma_f32 v[38:39], v[162:163], v[186:187], v[38:39] op_sel_hi:[0,1,1]
	v_pk_fma_f32 v[30:31], v[162:163], v[186:187], v[30:31] op_sel:[1,0,0] op_sel_hi:[1,1,1]
	v_pk_fma_f32 v[28:29], v[164:165], v[186:187], v[28:29] op_sel_hi:[0,1,1]
	v_pk_fma_f32 v[24:25], v[164:165], v[186:187], v[24:25] op_sel:[1,0,0] op_sel_hi:[1,1,1]
	v_pk_fma_f32 v[48:49], v[162:163], v[188:189], v[48:49] op_sel_hi:[0,1,1]
	v_pk_fma_f32 v[46:47], v[162:163], v[188:189], v[46:47] op_sel:[1,0,0] op_sel_hi:[1,1,1]
	v_pk_fma_f32 v[44:45], v[164:165], v[188:189], v[44:45] op_sel_hi:[0,1,1]
	v_pk_fma_f32 v[40:41], v[164:165], v[188:189], v[40:41] op_sel:[1,0,0] op_sel_hi:[1,1,1]
	v_pk_fma_f32 v[18:19], v[162:163], v[190:191], v[18:19] op_sel_hi:[0,1,1]
	v_pk_fma_f32 v[16:17], v[162:163], v[190:191], v[16:17] op_sel:[1,0,0] op_sel_hi:[1,1,1]
	v_pk_fma_f32 v[14:15], v[164:165], v[190:191], v[14:15] op_sel_hi:[0,1,1]
	v_pk_fma_f32 v[12:13], v[164:165], v[190:191], v[12:13] op_sel:[1,0,0] op_sel_hi:[1,1,1]
	s_waitcnt vmcnt(4) lgkmcnt(4)
	v_pk_fma_f32 v[50:51], v[166:167], v[192:193], v[50:51] op_sel_hi:[0,1,1]
	v_pk_fma_f32 v[26:27], v[166:167], v[192:193], v[26:27] op_sel:[1,0,0] op_sel_hi:[1,1,1]
	v_pk_fma_f32 v[22:23], v[168:169], v[192:193], v[22:23] op_sel_hi:[0,1,1]
	v_pk_fma_f32 v[20:21], v[168:169], v[192:193], v[20:21] op_sel:[1,0,0] op_sel_hi:[1,1,1]
	v_pk_fma_f32 v[38:39], v[166:167], v[194:195], v[38:39] op_sel_hi:[0,1,1]
	v_pk_fma_f32 v[30:31], v[166:167], v[194:195], v[30:31] op_sel:[1,0,0] op_sel_hi:[1,1,1]
	v_pk_fma_f32 v[28:29], v[168:169], v[194:195], v[28:29] op_sel_hi:[0,1,1]
	v_pk_fma_f32 v[24:25], v[168:169], v[194:195], v[24:25] op_sel:[1,0,0] op_sel_hi:[1,1,1]
	v_pk_fma_f32 v[48:49], v[166:167], v[196:197], v[48:49] op_sel_hi:[0,1,1]
	v_pk_fma_f32 v[46:47], v[166:167], v[196:197], v[46:47] op_sel:[1,0,0] op_sel_hi:[1,1,1]
	v_pk_fma_f32 v[44:45], v[168:169], v[196:197], v[44:45] op_sel_hi:[0,1,1]
	v_pk_fma_f32 v[40:41], v[168:169], v[196:197], v[40:41] op_sel:[1,0,0] op_sel_hi:[1,1,1]
	v_pk_fma_f32 v[18:19], v[166:167], v[198:199], v[18:19] op_sel_hi:[0,1,1]
	v_pk_fma_f32 v[16:17], v[166:167], v[198:199], v[16:17] op_sel:[1,0,0] op_sel_hi:[1,1,1]
	v_pk_fma_f32 v[14:15], v[168:169], v[198:199], v[14:15] op_sel_hi:[0,1,1]
	v_pk_fma_f32 v[12:13], v[168:169], v[198:199], v[12:13] op_sel:[1,0,0] op_sel_hi:[1,1,1]
	s_waitcnt vmcnt(0) lgkmcnt(0)
	v_pk_fma_f32 v[50:51], v[170:171], v[174:175], v[50:51] op_sel_hi:[0,1,1]
	v_pk_fma_f32 v[26:27], v[170:171], v[174:175], v[26:27] op_sel:[1,0,0] op_sel_hi:[1,1,1]
	v_pk_fma_f32 v[22:23], v[172:173], v[174:175], v[22:23] op_sel_hi:[0,1,1]
	v_pk_fma_f32 v[20:21], v[172:173], v[174:175], v[20:21] op_sel:[1,0,0] op_sel_hi:[1,1,1]
	v_pk_fma_f32 v[38:39], v[170:171], v[176:177], v[38:39] op_sel_hi:[0,1,1]
	v_pk_fma_f32 v[30:31], v[170:171], v[176:177], v[30:31] op_sel:[1,0,0] op_sel_hi:[1,1,1]
	v_pk_fma_f32 v[28:29], v[172:173], v[176:177], v[28:29] op_sel_hi:[0,1,1]
	v_pk_fma_f32 v[24:25], v[172:173], v[176:177], v[24:25] op_sel:[1,0,0] op_sel_hi:[1,1,1]
	v_pk_fma_f32 v[48:49], v[170:171], v[180:181], v[48:49] op_sel_hi:[0,1,1]
	v_pk_fma_f32 v[46:47], v[170:171], v[180:181], v[46:47] op_sel:[1,0,0] op_sel_hi:[1,1,1]
	v_pk_fma_f32 v[44:45], v[172:173], v[180:181], v[44:45] op_sel_hi:[0,1,1]
	v_pk_fma_f32 v[40:41], v[172:173], v[180:181], v[40:41] op_sel:[1,0,0] op_sel_hi:[1,1,1]
	v_pk_fma_f32 v[18:19], v[170:171], v[182:183], v[18:19] op_sel_hi:[0,1,1]
	v_pk_fma_f32 v[16:17], v[170:171], v[182:183], v[16:17] op_sel:[1,0,0] op_sel_hi:[1,1,1]
	v_pk_fma_f32 v[14:15], v[172:173], v[182:183], v[14:15] op_sel_hi:[0,1,1]
	v_pk_fma_f32 v[12:13], v[172:173], v[182:183], v[12:13] op_sel:[1,0,0] op_sel_hi:[1,1,1]
	v_add_u32_e32 v253, 0x200, v253
	s_add_u32 s4, s4, 0x20000
	s_addc_u32 s5, s5, 0
	s_cmp_eq_u32 s4, 0x80000
	s_cbranch_scc0 .LBB0_543
	v_cvt_f32_i32_e32 v4, s2
	s_ashr_i32 s5, s2, 31
	s_mov_b32 s4, s2
	s_lshl_b64 s[2:3], s[4:5], 14
	v_mul_f32_e32 v4, 0xc1447cbd, v4
	v_div_scale_f32 v32, s[8:9], s48, s48, v4
	v_rcp_f32_e32 v33, v32
	v_div_scale_f32 v34, vcc, v4, s48, v4
	s_add_u32 s2, s14, s2
	v_fma_f32 v36, -v32, v33, 1.0
	v_fmac_f32_e32 v33, v36, v33
	v_mul_f32_e32 v36, v34, v33
	v_fma_f32 v42, -v32, v36, v34
	v_fmac_f32_e32 v36, v42, v33
	v_fma_f32 v32, -v32, v36, v34
	v_div_fmas_f32 v32, v32, v33, v36
	v_div_fixup_f32 v4, v32, s48, v4
	v_add_f32_e32 v34, 0xc0447cbd, v4
	v_mul_f32_e64 v4, v1, |v34|
	v_mul_f32_e32 v32, 0x3fb8aa3b, v4
	v_fma_f32 v33, v4, s49, -v32
	v_rndne_f32_e32 v36, v32
	v_fmac_f32_e32 v33, 0x32a5705f, v4
	v_sub_f32_e32 v32, v32, v36
	v_add_f32_e32 v32, v32, v33
	v_exp_f32_e32 v32, v32
	v_cvt_i32_f32_e32 v33, v36
	v_cmp_ngt_f32_e32 vcc, s52, v4
	s_addc_u32 s3, s15, s3
	v_ldexp_f32 v32, v32, v33
	v_cndmask_b32_e32 v32, 0, v32, vcc
	v_cmp_nlt_f32_e32 vcc, s53, v4
	v_lshlrev_b32_e32 v4, 1, v0
	s_nop 0
	v_cndmask_b32_e32 v36, v217, v32, vcc
	v_mul_f32_e32 v33, v36, v51
	v_lshlrev_b32_e32 v32, 1, v6
	s_and_saveexec_b64 s[8:9], s[86:87]
	s_xor_b64 s[8:9], exec, s[8:9]
	s_cbranch_execz .LBB0_546
	v_bfe_u32 v43, v33, 16, 1
	v_mul_f32_e32 v42, v36, v50
	v_add3_u32 v33, v33, v43, s54
	global_store_short_d16_hi v32, v33, s[2:3] offset:2048
	v_bfe_u32 v33, v42, 16, 1
	v_add3_u32 v33, v42, v33, s54
	global_store_short_d16_hi v4, v33, s[2:3] offset:4094
